# RWKV-7 state scan: second step's state-side fragment and decay reads issued under the first step's matrix ops instead of after them
# baseline (speedup 1.0000x reference)
.LBB0_433:
	s_mul_i32 s1, s0, 37
	s_bfe_u32 s2, s1, 0x80008
	s_lshr_b32 s1, s1, 8
	s_sub_i32 s1, s0, s1
	s_bfe_u32 s1, s1, 0x70001
	s_add_i32 s1, s1, s2
	s_bfe_u32 s1, s1, 0x60002
	s_mul_i32 s1, s1, 7
	s_sub_i32 s1, s0, s1
	s_and_b32 s1, s1, 0xff
	s_mulk_i32 s1, 0x4800
	v_add_u32_e32 v136, s1, v151
	ds_read_b128 v[32:35], v136 offset:17792
	ds_read_b128 v[36:39], v136 offset:17824
	ds_read_b128 v[40:43], v136 offset:17856
	ds_read_b128 v[44:47], v136 offset:17888
	ds_read_b128 v[128:131], v136 offset:17920
	ds_read_b128 v[132:135], v136 offset:17952
	ds_read_b128 v[220:223], v136 offset:17984
	ds_read_b128 v[224:227], v136 offset:18016
	v_cvt_pk_bf16_f32 v112, v16, v17
	v_cvt_pk_bf16_f32 v113, v18, v19
	v_cvt_pk_bf16_f32 v114, v20, v21
	v_cvt_pk_bf16_f32 v115, v22, v23
	v_cvt_pk_bf16_f32 v116, v24, v25
	v_cvt_pk_bf16_f32 v117, v26, v27
	v_cvt_pk_bf16_f32 v118, v28, v29
	v_cvt_pk_bf16_f32 v119, v30, v31
	v_cvt_pk_bf16_f32 v120, v0, v1
	v_cvt_pk_bf16_f32 v121, v2, v3
	v_cvt_pk_bf16_f32 v122, v4, v5
	v_cvt_pk_bf16_f32 v123, v6, v7
	v_cvt_pk_bf16_f32 v124, v8, v9
	v_cvt_pk_bf16_f32 v125, v10, v11
	v_cvt_pk_bf16_f32 v126, v12, v13
	v_cvt_pk_bf16_f32 v127, v14, v15
	s_waitcnt lgkmcnt(0)
	v_pk_mul_f32 v[16:17], v[16:17], v[32:33]
	v_pk_mul_f32 v[18:19], v[18:19], v[34:35]
	v_pk_mul_f32 v[20:21], v[20:21], v[36:37]
	v_pk_mul_f32 v[22:23], v[22:23], v[38:39]
	v_pk_mul_f32 v[24:25], v[24:25], v[40:41]
	v_pk_mul_f32 v[26:27], v[26:27], v[42:43]
	v_pk_mul_f32 v[28:29], v[28:29], v[44:45]
	v_pk_mul_f32 v[30:31], v[30:31], v[46:47]
	v_mfma_f32_32x32x16_bf16 v[32:47], v[48:51], v[112:115], 0
	v_mul_f32_e64 v0, v0, v128
	v_mul_f32_e64 v1, v1, v129
	v_mul_f32_e64 v2, v2, v130
	v_mul_f32_e64 v3, v3, v131
	v_mul_f32_e64 v4, v4, v132
	v_mul_f32_e64 v5, v5, v133
	v_pk_mul_f32 v[6:7], v[6:7], v[134:135]
	s_or_b32 s1, s0, 1
	v_mfma_f32_32x32x16_bf16 v[16:31], v[72:75], v[112:115], v[16:31]
	s_and_b32 s2, s1, 0xff
	v_mul_f32_e64 v8, v8, v220
	v_mul_f32_e64 v9, v9, v221
	v_mul_f32_e64 v10, v10, v222
	v_mul_f32_e64 v11, v11, v223
	v_pk_mul_f32 v[12:13], v[12:13], v[224:225]
	v_pk_mul_f32 v[14:15], v[14:15], v[226:227]
	s_mul_i32 s2, s2, 37
	s_lshr_b32 s2, s2, 8
	v_mfma_f32_32x32x16_bf16 v[32:47], v[52:55], v[116:119], v[32:47]
	s_sub_i32 s3, s1, s2
	s_bfe_u32 s3, s3, 0x70001
	s_add_i32 s3, s3, s2
	s_lshr_b32 s2, s3, 2
	s_mul_i32 s2, s2, 7
	s_sub_i32 s1, s1, s2
	s_and_b32 s1, s1, 0xff
	v_mfma_f32_32x32x16_bf16 v[0:15], v[88:91], v[112:115], v[0:15]
	s_mulk_i32 s1, 0x4800
	s_add_i32 s1, s1, 0
	v_add_u32_e32 v192, s1, v144
	v_add_u32_e32 v180, v192, v156
	v_add_u32_e32 v228, s1, v153
	v_add_u32_e32 v228, v228, v155
	v_add_u32_e32 v229, 0x800, v228
	v_add_u32_e32 v230, 0x1800, v228
	v_add_u32_e32 v231, v192, v154
	ds_read_b128 v[128:131], v231 offset:2176
	ds_read2_b64 v[140:143], v229 offset0:116 offset1:118
	ds_read2_b64 v[136:139], v229 offset0:120 offset1:122
	ds_read2_b64 v[132:135], v229 offset0:124 offset1:126
	ds_read2_b64 v[160:163], v230 offset0:144 offset1:146
	ds_read2_b64 v[164:167], v230 offset0:148 offset1:150
	ds_read2_b64 v[168:171], v230 offset0:152 offset1:154
	ds_read2_b64 v[172:175], v230 offset0:156 offset1:158
	ds_read_b128 v[176:179], v180 offset:11648
	ds_read_b128 v[180:183], v180 offset:13184
	ds_read_b128 v[220:223], v192 offset:17888
	ds_read_b128 v[224:227], v192 offset:17856
	ds_read_b128 v[228:231], v192 offset:17824
	ds_read_b128 v[232:235], v192 offset:17792
	ds_read_b128 v[236:239], v192 offset:18016
	ds_read_b128 v[240:243], v192 offset:17984
	ds_read_b128 v[244:247], v192 offset:17952
	s_cmpk_gt_u32 s0, 0x7d
	s_cselect_b64 s[2:3], -1, 0
	v_mfma_f32_32x32x16_bf16 v[16:31], v[76:79], v[116:119], v[16:31]
	s_and_b64 vcc, exec, s[2:3]
	v_mfma_f32_32x32x16_bf16 v[32:47], v[56:59], v[120:123], v[32:47]
	v_mfma_f32_32x32x16_bf16 v[0:15], v[92:95], v[116:119], v[0:15]
	v_mfma_f32_32x32x16_bf16 v[16:31], v[80:83], v[120:123], v[16:31]
	v_mfma_f32_32x32x16_bf16 v[32:47], v[60:63], v[124:127], v[32:47]
	v_mfma_f32_32x32x16_bf16 v[0:15], v[96:99], v[120:123], v[0:15]
	v_mfma_f32_32x32x16_bf16 v[16:31], v[84:87], v[124:127], v[16:31]
	v_mfma_f32_32x32x16_bf16 v[32:47], v[68:71], v[64:67], v[32:47]
	v_mfma_f32_32x32x16_bf16 v[0:15], v[100:103], v[124:127], v[0:15]
	s_nop 10
	v_add_u32_e32 v45, s1, v153
	v_add_u32_e32 v46, v45, v152
	v_add_u32_e32 v44, v192, v150
	ds_read2_b64 v[40:43], v46 offset1:2
	ds_read2_b64 v[116:119], v46 offset0:4 offset1:6
	ds_read2_b64 v[120:123], v46 offset0:8 offset1:10
	ds_read2_b64 v[124:127], v46 offset0:12 offset1:14
	v_add_u32_e32 v46, v45, v155
	v_add_u32_e32 v46, 0x800, v46
	v_mfma_f32_32x32x16_bf16 v[16:31], v[104:107], v[64:67], v[16:31]
	ds_read_b128 v[112:115], v44 offset:14720
	ds_read2_b64 v[44:47], v46 offset0:112 offset1:114
	ds_write2st64_b32 v158, v32, v33 offset1:1
	ds_write2st64_b32 v158, v34, v35 offset0:2 offset1:3
	ds_write2st64_b32 v158, v36, v37 offset0:8 offset1:9
	ds_write2st64_b32 v158, v38, v39 offset0:10 offset1:11
	s_waitcnt lgkmcnt(0)
	s_barrier
	ds_read_b128 v[36:39], v192 offset:17920
	v_cvt_pk_bf16_f32 v32, v16, v17
	v_mfma_f32_32x32x16_bf16 v[0:15], v[108:111], v[64:67], v[0:15]
	v_cvt_pk_bf16_f32 v33, v18, v19
	v_cvt_pk_bf16_f32 v34, v20, v21
	v_cvt_pk_bf16_f32 v35, v22, v23
	v_cvt_pk_bf16_f32 v184, v24, v25
	v_cvt_pk_bf16_f32 v185, v26, v27
	v_cvt_pk_bf16_f32 v186, v28, v29
	v_cvt_pk_bf16_f32 v187, v30, v31
	v_cvt_pk_bf16_f32 v188, v0, v1
	v_cvt_pk_bf16_f32 v189, v2, v3
	v_cvt_pk_bf16_f32 v190, v4, v5
	v_cvt_pk_bf16_f32 v191, v6, v7
	v_cvt_pk_bf16_f32 v216, v8, v9
	v_cvt_pk_bf16_f32 v217, v10, v11
	v_cvt_pk_bf16_f32 v218, v12, v13
	v_cvt_pk_bf16_f32 v219, v14, v15
	v_pk_mul_f32 v[28:29], v[28:29], v[220:221]
	v_pk_mul_f32 v[30:31], v[30:31], v[222:223]
	v_pk_mul_f32 v[24:25], v[24:25], v[224:225]
	v_pk_mul_f32 v[26:27], v[26:27], v[226:227]
	v_pk_mul_f32 v[20:21], v[20:21], v[228:229]
	v_pk_mul_f32 v[22:23], v[22:23], v[230:231]
	v_pk_mul_f32 v[18:19], v[18:19], v[234:235]
	v_pk_mul_f32 v[16:17], v[16:17], v[232:233]
	v_pk_mul_f32 v[12:13], v[12:13], v[236:237]
	v_pk_mul_f32 v[14:15], v[14:15], v[238:239]
	v_mfma_f32_32x32x16_bf16 v[16:31], v[44:47], v[32:35], v[16:31]
	v_mul_f32_e64 v8, v8, v240
	v_mul_f32_e64 v9, v9, v241
	v_mul_f32_e64 v10, v10, v242
	v_mul_f32_e64 v11, v11, v243
	v_pk_mul_f32 v[4:5], v[4:5], v[244:245]
	v_pk_mul_f32 v[6:7], v[6:7], v[246:247]
	v_mfma_f32_32x32x16_bf16 v[16:31], v[140:143], v[184:187], v[16:31]
	s_waitcnt lgkmcnt(0)
	v_mul_f32_e64 v2, v2, v38
	v_mul_f32_e64 v3, v3, v39
	v_mul_f32_e64 v0, v0, v36
	v_mul_f32_e64 v1, v1, v37
	s_nop 1
	v_mfma_f32_32x32x16_bf16 v[0:15], v[160:163], v[32:35], v[0:15]
	v_mfma_f32_32x32x16_bf16 v[32:47], v[40:43], v[32:35], 0
	v_mfma_f32_32x32x16_bf16 v[32:47], v[116:119], v[184:187], v[32:47]
	v_mfma_f32_32x32x16_bf16 v[0:15], v[164:167], v[184:187], v[0:15]
	v_mfma_f32_32x32x16_bf16 v[32:47], v[120:123], v[188:191], v[32:47]
	v_mfma_f32_32x32x16_bf16 v[16:31], v[136:139], v[188:191], v[16:31]
	v_mfma_f32_32x32x16_bf16 v[0:15], v[168:171], v[188:191], v[0:15]
	v_mfma_f32_32x32x16_bf16 v[32:47], v[124:127], v[216:219], v[32:47]
	v_mfma_f32_32x32x16_bf16 v[16:31], v[132:135], v[216:219], v[16:31]
	v_mfma_f32_32x32x16_bf16 v[0:15], v[172:175], v[216:219], v[0:15]
	v_mfma_f32_32x32x16_bf16 v[32:47], v[128:131], v[112:115], v[32:47]
	v_mfma_f32_32x32x16_bf16 v[16:31], v[176:179], v[112:115], v[16:31]
	v_mfma_f32_32x32x16_bf16 v[0:15], v[180:183], v[112:115], v[0:15]
	s_cbranch_vccnz .LBB0_432
	s_add_i32 s1, s0, 2
	s_and_b32 s4, s1, 0xff
	s_mul_i32 s4, s4, 37
	s_lshr_b32 s5, s4, 8
	s_sub_i32 s5, s1, s5
	s_bfe_u32 s5, s5, 0x70001
	s_bfe_u32 s4, s4, 0x80008
	s_add_i32 s5, s5, s4
	s_bfe_u32 s4, s5, 0x60002
	s_mul_i32 s4, s4, 7
	s_sub_i32 s1, s1, s4
	s_and_b32 s1, s1, 0xff
	s_mulk_i32 s1, 0x4800
	s_add_i32 s1, s1, 0
	v_add_u32_e32 v40, s1, v144
	v_add_u32_e32 v42, s1, v153
	v_add_u32_e32 v41, v40, v150
	v_add_u32_e32 v43, v42, v152
	ds_read2_b64 v[48:51], v43 offset1:2
	ds_read2_b64 v[52:55], v43 offset0:4 offset1:6
	ds_read2_b64 v[56:59], v43 offset0:8 offset1:10
	ds_read2_b64 v[60:63], v43 offset0:12 offset1:14
	v_add_u32_e32 v43, v40, v154
	ds_read_b128 v[64:67], v41 offset:14720
	ds_read_b128 v[68:71], v43 offset:2176
	v_add_u32_e32 v41, v42, v155
	v_add_u32_e32 v42, 0x800, v41
	v_add_u32_e32 v41, 0x1800, v41
	ds_read2_b64 v[72:75], v42 offset0:112 offset1:114
	ds_read2_b64 v[76:79], v42 offset0:116 offset1:118
	ds_read2_b64 v[80:83], v42 offset0:120 offset1:122
	ds_read2_b64 v[84:87], v42 offset0:124 offset1:126
	v_add_u32_e32 v40, v40, v156
	ds_read2_b64 v[88:91], v41 offset0:144 offset1:146
	ds_read2_b64 v[92:95], v41 offset0:148 offset1:150
	ds_read2_b64 v[96:99], v41 offset0:152 offset1:154
	ds_read2_b64 v[100:103], v41 offset0:156 offset1:158
	ds_read_b128 v[104:107], v40 offset:11648
	ds_read_b128 v[108:111], v40 offset:13184
	s_branch .LBB0_432
